# P4 epilogue: 16 sigmoid-gate loads issued up front with counted waits instead of a load-wait-store ladder
# baseline (speedup 1.0000x reference)
.LBB0_661:
	v_mul_f32_e32 v1, 0x41800000, v128
	v_ashrrev_i32_e32 v167, 31, v166
	v_ashrrev_i32_e32 v165, 31, v164
	v_lshlrev_b64 v[2:3], 12, v[166:167]
	v_lshl_add_u64 v[132:133], s[8:9], 0, v[2:3]
	v_lshlrev_b64 v[2:3], 1, v[164:165]
	v_lshl_add_u64 v[136:137], v[132:133], 0, v[2:3]
	s_mov_b64 s[96:97], 0x10000
	s_mov_b64 s[98:99], 0x50000
	v_mov_b64_e32 v[252:253], v[136:137]
	global_load_dwordx4 v[180:183], v[252:253], off
	global_load_dwordx4 v[184:187], v[252:253], off offset:256
	v_lshl_add_u64 v[252:253], v[252:253], 0, s[96:97]
	global_load_dwordx4 v[188:191], v[252:253], off
	global_load_dwordx4 v[192:195], v[252:253], off offset:256
	v_lshl_add_u64 v[252:253], v[252:253], 0, s[96:97]
	global_load_dwordx4 v[196:199], v[252:253], off
	global_load_dwordx4 v[200:203], v[252:253], off offset:256
	v_lshl_add_u64 v[252:253], v[252:253], 0, s[96:97]
	global_load_dwordx4 v[204:207], v[252:253], off
	global_load_dwordx4 v[208:211], v[252:253], off offset:256
	v_lshl_add_u64 v[252:253], v[252:253], 0, s[98:99]
	global_load_dwordx4 v[212:215], v[252:253], off
	global_load_dwordx4 v[216:219], v[252:253], off offset:256
	v_lshl_add_u64 v[252:253], v[252:253], 0, s[96:97]
	global_load_dwordx4 v[220:223], v[252:253], off
	global_load_dwordx4 v[224:227], v[252:253], off offset:256
	v_lshl_add_u64 v[252:253], v[252:253], 0, s[96:97]
	global_load_dwordx4 v[234:237], v[252:253], off
	global_load_dwordx4 v[238:241], v[252:253], off offset:256
	v_lshl_add_u64 v[252:253], v[252:253], 0, s[96:97]
	global_load_dwordx4 v[244:247], v[252:253], off
	global_load_dwordx4 v[248:251], v[252:253], off offset:256
	v_mul_f32_e32 v138, 0x41800000, v129
	v_mul_f32_e32 v124, 0x41800000, v124
	v_mul_f32_e32 v125, 0x41800000, v125
	v_mov_b32_e32 v128, 0
	v_mov_b32_e32 v129, 0
	v_mul_f32_e32 v130, 0x41800000, v130
	v_mul_f32_e32 v131, 0x41800000, v131
	v_mul_f32_e32 v126, 0x41800000, v126
	v_mul_f32_e32 v127, 0x41800000, v127
	v_mul_f32_e32 v116, 0x41800000, v116
	v_mul_f32_e32 v117, 0x41800000, v117
	v_mul_f32_e32 v118, 0x41800000, v118
	v_mul_f32_e32 v119, 0x41800000, v119
	v_mul_f32_e32 v108, 0x41800000, v108
	v_mul_f32_e32 v109, 0x41800000, v109
	v_mul_f32_e32 v114, 0x41800000, v114
	v_mul_f32_e32 v115, 0x41800000, v115
	v_mul_f32_e32 v110, 0x41800000, v110
	v_mul_f32_e32 v111, 0x41800000, v111
	v_mul_f32_e32 v100, 0x41800000, v100
	v_mul_f32_e32 v101, 0x41800000, v101
	v_mul_f32_e32 v102, 0x41800000, v102
	v_mul_f32_e32 v103, 0x41800000, v103
	v_mul_f32_e32 v92, 0x41800000, v92
	v_mul_f32_e32 v93, 0x41800000, v93
	v_mul_f32_e32 v98, 0x41800000, v98
	v_mul_f32_e32 v99, 0x41800000, v99
	v_mul_f32_e32 v94, 0x41800000, v94
	v_mul_f32_e32 v95, 0x41800000, v95
	v_mul_f32_e32 v84, 0x41800000, v84
	v_mul_f32_e32 v85, 0x41800000, v85
	v_mul_f32_e32 v86, 0x41800000, v86
	v_mul_f32_e32 v87, 0x41800000, v87
	v_mul_f32_e32 v76, 0x41800000, v76
	v_mul_f32_e32 v77, 0x41800000, v77
	v_mul_f32_e32 v82, 0x41800000, v82
	v_mul_f32_e32 v83, 0x41800000, v83
	v_mul_f32_e32 v78, 0x41800000, v78
	v_mul_f32_e32 v79, 0x41800000, v79
	v_mul_f32_e32 v68, 0x41800000, v68
	v_mul_f32_e32 v69, 0x41800000, v69
	v_mul_f32_e32 v70, 0x41800000, v70
	v_mul_f32_e32 v71, 0x41800000, v71
	v_mul_f32_e32 v60, 0x41800000, v60
	v_mul_f32_e32 v61, 0x41800000, v61
	v_mul_f32_e32 v66, 0x41800000, v66
	v_mul_f32_e32 v67, 0x41800000, v67
	v_mul_f32_e32 v62, 0x41800000, v62
	v_mul_f32_e32 v63, 0x41800000, v63
	v_mul_f32_e32 v52, 0x41800000, v52
	v_mul_f32_e32 v53, 0x41800000, v53
	v_mul_f32_e32 v54, 0x41800000, v54
	v_mul_f32_e32 v55, 0x41800000, v55
	v_mul_f32_e32 v44, 0x41800000, v44
	v_mul_f32_e32 v45, 0x41800000, v45
	v_mul_f32_e32 v50, 0x41800000, v50
	v_mul_f32_e32 v51, 0x41800000, v51
	v_mul_f32_e32 v46, 0x41800000, v46
	v_mul_f32_e32 v47, 0x41800000, v47
	v_mul_f32_e32 v36, 0x41800000, v36
	v_mul_f32_e32 v37, 0x41800000, v37
	v_mul_f32_e32 v38, 0x41800000, v38
	v_mul_f32_e32 v39, 0x41800000, v39
	v_mul_f32_e32 v28, 0x41800000, v28
	v_mul_f32_e32 v29, 0x41800000, v29
	v_mul_f32_e32 v34, 0x41800000, v34
	v_mul_f32_e32 v35, 0x41800000, v35
	v_mul_f32_e32 v30, 0x41800000, v30
	v_mul_f32_e32 v31, 0x41800000, v31
	v_mul_f32_e32 v20, 0x41800000, v20
	v_mul_f32_e32 v21, 0x41800000, v21
	v_mul_f32_e32 v22, 0x41800000, v22
	v_mul_f32_e32 v23, 0x41800000, v23
	v_mul_f32_e32 v12, 0x41800000, v12
	v_mul_f32_e32 v13, 0x41800000, v13
	v_mul_f32_e32 v18, 0x41800000, v18
	v_mul_f32_e32 v19, 0x41800000, v19
	v_mul_f32_e32 v14, 0x41800000, v14
	v_mul_f32_e32 v15, 0x41800000, v15
	s_waitcnt vmcnt(15)
	v_lshlrev_b32_e32 v139, 16, v180
	v_and_b32_e32 v132, 0xffff0000, v180
	v_lshlrev_b32_e32 v141, 16, v182
	v_and_b32_e32 v134, 0xffff0000, v182
	v_mul_f32_e32 v1, v1, v139
	v_mul_f32_e32 v132, v138, v132
	v_mul_f32_e32 v124, v124, v141
	v_mul_f32_e32 v125, v125, v134
	v_cvt_pk_fp8_f32 v128, v1, v132
	v_cvt_pk_fp8_f32 v129, v124, v125
	v_lshlrev_b32_e32 v140, 16, v181
	v_and_b32_e32 v133, 0xffff0000, v181
	v_lshlrev_b32_e32 v142, 16, v183
	v_and_b32_e32 v135, 0xffff0000, v183
	v_mul_f32_e32 v130, v130, v140
	v_mul_f32_e32 v131, v131, v133
	v_mul_f32_e32 v1, v126, v142
	v_mul_f32_e32 v124, v127, v135
	v_cvt_pk_fp8_f32 v128, v130, v131 op_sel:[0,0,1]
	v_cvt_pk_fp8_f32 v129, v1, v124 op_sel:[0,0,1]
	v_lshlrev_b64 v[124:125], 11, v[166:167]
	v_lshl_add_u64 v[124:125], s[10:11], 0, v[124:125]
	v_lshl_add_u64 v[130:131], v[124:125], 0, v[164:165]
	global_store_dwordx2 v[130:131], v[128:129], off
	v_mul_f32_e32 v1, 0x41800000, v120
	v_mul_f32_e32 v128, 0x41800000, v121
	v_mov_b32_e32 v120, 0
	v_mov_b32_e32 v121, 0
	v_mul_f32_e32 v129, 0x41800000, v122
	v_mul_f32_e32 v132, 0x41800000, v123
	v_add_u32_e32 v122, 16, v166
	v_ashrrev_i32_e32 v123, 31, v122
	v_mul_f32_e32 v4, 0x41800000, v4
	v_mul_f32_e32 v5, 0x41800000, v5
	v_mul_f32_e32 v6, 0x41800000, v6
	v_mul_f32_e32 v7, 0x41800000, v7
	s_andn2_b64 vcc, exec, s[0:1]
	s_mov_b64 s[0:1], -1
	s_waitcnt vmcnt(15)
	v_lshlrev_b32_e32 v133, 16, v184
	v_and_b32_e32 v124, 0xffff0000, v184
	v_lshlrev_b32_e32 v135, 16, v186
	v_and_b32_e32 v126, 0xffff0000, v186
	v_mul_f32_e32 v1, v1, v133
	v_mul_f32_e32 v124, v128, v124
	v_mul_f32_e32 v116, v116, v135
	v_mul_f32_e32 v117, v117, v126
	v_cvt_pk_fp8_f32 v120, v1, v124
	v_cvt_pk_fp8_f32 v121, v116, v117
	v_lshlrev_b32_e32 v134, 16, v185
	v_and_b32_e32 v125, 0xffff0000, v185
	v_lshlrev_b32_e32 v136, 16, v187
	v_and_b32_e32 v127, 0xffff0000, v187
	v_mul_f32_e32 v128, v129, v134
	v_mul_f32_e32 v125, v132, v125
	v_mul_f32_e32 v1, v118, v136
	v_mul_f32_e32 v116, v119, v127
	v_cvt_pk_fp8_f32 v120, v128, v125 op_sel:[0,0,1]
	v_cvt_pk_fp8_f32 v121, v1, v116 op_sel:[0,0,1]
	v_lshlrev_b64 v[116:117], 12, v[122:123]
	v_lshl_add_u64 v[116:117], s[8:9], 0, v[116:117]
	v_lshl_add_u64 v[124:125], v[116:117], 0, v[2:3]
	global_store_dwordx2 v[130:131], v[120:121], off offset:128
	v_mul_f32_e32 v1, 0x41800000, v112
	v_mul_f32_e32 v120, 0x41800000, v113
	v_mov_b32_e32 v112, 0
	v_mov_b32_e32 v113, 0
	s_waitcnt vmcnt(15)
	v_lshlrev_b32_e32 v121, 16, v188
	v_and_b32_e32 v116, 0xffff0000, v188
	v_lshlrev_b32_e32 v127, 16, v190
	v_and_b32_e32 v118, 0xffff0000, v190
	v_mul_f32_e32 v1, v1, v121
	v_mul_f32_e32 v116, v120, v116
	v_mul_f32_e32 v108, v108, v127
	v_mul_f32_e32 v109, v109, v118
	v_cvt_pk_fp8_f32 v112, v1, v116
	v_cvt_pk_fp8_f32 v113, v108, v109
	v_lshlrev_b32_e32 v126, 16, v189
	v_and_b32_e32 v117, 0xffff0000, v189
	v_lshlrev_b32_e32 v128, 16, v191
	v_and_b32_e32 v119, 0xffff0000, v191
	v_mul_f32_e32 v114, v114, v126
	v_mul_f32_e32 v115, v115, v117
	v_mul_f32_e32 v1, v110, v128
	v_mul_f32_e32 v108, v111, v119
	v_cvt_pk_fp8_f32 v112, v114, v115 op_sel:[0,0,1]
	v_cvt_pk_fp8_f32 v113, v1, v108 op_sel:[0,0,1]
	v_lshlrev_b64 v[108:109], 11, v[122:123]
	v_lshl_add_u64 v[108:109], s[10:11], 0, v[108:109]
	v_lshl_add_u64 v[114:115], v[108:109], 0, v[164:165]
	global_store_dwordx2 v[114:115], v[112:113], off
	v_mul_f32_e32 v1, 0x41800000, v104
	v_mul_f32_e32 v112, 0x41800000, v105
	v_mov_b32_e32 v104, 0
	v_mov_b32_e32 v105, 0
	v_mul_f32_e32 v113, 0x41800000, v106
	v_mul_f32_e32 v116, 0x41800000, v107
	v_add_u32_e32 v106, 32, v166
	v_ashrrev_i32_e32 v107, 31, v106
	s_waitcnt vmcnt(15)
	v_lshlrev_b32_e32 v117, 16, v192
	v_and_b32_e32 v108, 0xffff0000, v192
	v_lshlrev_b32_e32 v119, 16, v194
	v_and_b32_e32 v110, 0xffff0000, v194
	v_mul_f32_e32 v1, v1, v117
	v_mul_f32_e32 v108, v112, v108
	v_mul_f32_e32 v100, v100, v119
	v_mul_f32_e32 v101, v101, v110
	v_cvt_pk_fp8_f32 v104, v1, v108
	v_cvt_pk_fp8_f32 v105, v100, v101
	v_lshlrev_b32_e32 v118, 16, v193
	v_and_b32_e32 v109, 0xffff0000, v193
	v_lshlrev_b32_e32 v120, 16, v195
	v_and_b32_e32 v111, 0xffff0000, v195
	v_mul_f32_e32 v112, v113, v118
	v_mul_f32_e32 v109, v116, v109
	v_mul_f32_e32 v1, v102, v120
	v_mul_f32_e32 v100, v103, v111
	v_cvt_pk_fp8_f32 v104, v112, v109 op_sel:[0,0,1]
	v_cvt_pk_fp8_f32 v105, v1, v100 op_sel:[0,0,1]
	v_lshlrev_b64 v[100:101], 12, v[106:107]
	v_lshl_add_u64 v[100:101], s[8:9], 0, v[100:101]
	v_lshl_add_u64 v[108:109], v[100:101], 0, v[2:3]
	global_store_dwordx2 v[114:115], v[104:105], off offset:128
	v_mul_f32_e32 v1, 0x41800000, v96
	v_mul_f32_e32 v104, 0x41800000, v97
	v_mov_b32_e32 v96, 0
	v_mov_b32_e32 v97, 0
	s_waitcnt vmcnt(15)
	v_lshlrev_b32_e32 v105, 16, v196
	v_and_b32_e32 v100, 0xffff0000, v196
	v_lshlrev_b32_e32 v111, 16, v198
	v_and_b32_e32 v102, 0xffff0000, v198
	v_mul_f32_e32 v1, v1, v105
	v_mul_f32_e32 v100, v104, v100
	v_mul_f32_e32 v92, v92, v111
	v_mul_f32_e32 v93, v93, v102
	v_cvt_pk_fp8_f32 v96, v1, v100
	v_cvt_pk_fp8_f32 v97, v92, v93
	v_lshlrev_b32_e32 v110, 16, v197
	v_and_b32_e32 v101, 0xffff0000, v197
	v_lshlrev_b32_e32 v112, 16, v199
	v_and_b32_e32 v103, 0xffff0000, v199
	v_mul_f32_e32 v98, v98, v110
	v_mul_f32_e32 v99, v99, v101
	v_mul_f32_e32 v1, v94, v112
	v_mul_f32_e32 v92, v95, v103
	v_cvt_pk_fp8_f32 v96, v98, v99 op_sel:[0,0,1]
	v_cvt_pk_fp8_f32 v97, v1, v92 op_sel:[0,0,1]
	v_lshlrev_b64 v[92:93], 11, v[106:107]
	v_lshl_add_u64 v[92:93], s[10:11], 0, v[92:93]
	v_lshl_add_u64 v[98:99], v[92:93], 0, v[164:165]
	global_store_dwordx2 v[98:99], v[96:97], off
	v_mul_f32_e32 v1, 0x41800000, v88
	v_mul_f32_e32 v96, 0x41800000, v89
	v_mov_b32_e32 v88, 0
	v_mov_b32_e32 v89, 0
	v_mul_f32_e32 v97, 0x41800000, v90
	v_mul_f32_e32 v100, 0x41800000, v91
	v_add_u32_e32 v90, 48, v166
	v_ashrrev_i32_e32 v91, 31, v90
	s_waitcnt vmcnt(15)
	v_lshlrev_b32_e32 v101, 16, v200
	v_and_b32_e32 v92, 0xffff0000, v200
	v_lshlrev_b32_e32 v103, 16, v202
	v_and_b32_e32 v94, 0xffff0000, v202
	v_mul_f32_e32 v1, v1, v101
	v_mul_f32_e32 v92, v96, v92
	v_mul_f32_e32 v84, v84, v103
	v_mul_f32_e32 v85, v85, v94
	v_cvt_pk_fp8_f32 v88, v1, v92
	v_cvt_pk_fp8_f32 v89, v84, v85
	v_lshlrev_b32_e32 v102, 16, v201
	v_and_b32_e32 v93, 0xffff0000, v201
	v_lshlrev_b32_e32 v104, 16, v203
	v_and_b32_e32 v95, 0xffff0000, v203
	v_mul_f32_e32 v96, v97, v102
	v_mul_f32_e32 v93, v100, v93
	v_mul_f32_e32 v1, v86, v104
	v_mul_f32_e32 v84, v87, v95
	v_cvt_pk_fp8_f32 v88, v96, v93 op_sel:[0,0,1]
	v_cvt_pk_fp8_f32 v89, v1, v84 op_sel:[0,0,1]
	v_lshlrev_b64 v[84:85], 12, v[90:91]
	v_lshl_add_u64 v[84:85], s[8:9], 0, v[84:85]
	v_lshl_add_u64 v[92:93], v[84:85], 0, v[2:3]
	global_store_dwordx2 v[98:99], v[88:89], off offset:128
	v_mul_f32_e32 v1, 0x41800000, v80
	v_mul_f32_e32 v88, 0x41800000, v81
	v_mov_b32_e32 v80, 0
	v_mov_b32_e32 v81, 0
	s_waitcnt vmcnt(15)
	v_lshlrev_b32_e32 v89, 16, v204
	v_and_b32_e32 v84, 0xffff0000, v204
	v_lshlrev_b32_e32 v95, 16, v206
	v_and_b32_e32 v86, 0xffff0000, v206
	v_mul_f32_e32 v1, v1, v89
	v_mul_f32_e32 v84, v88, v84
	v_mul_f32_e32 v76, v76, v95
	v_mul_f32_e32 v77, v77, v86
	v_cvt_pk_fp8_f32 v80, v1, v84
	v_cvt_pk_fp8_f32 v81, v76, v77
	v_lshlrev_b32_e32 v94, 16, v205
	v_and_b32_e32 v85, 0xffff0000, v205
	v_lshlrev_b32_e32 v96, 16, v207
	v_and_b32_e32 v87, 0xffff0000, v207
	v_mul_f32_e32 v82, v82, v94
	v_mul_f32_e32 v83, v83, v85
	v_mul_f32_e32 v1, v78, v96
	v_mul_f32_e32 v76, v79, v87
	v_cvt_pk_fp8_f32 v80, v82, v83 op_sel:[0,0,1]
	v_cvt_pk_fp8_f32 v81, v1, v76 op_sel:[0,0,1]
	v_lshlrev_b64 v[76:77], 11, v[90:91]
	v_lshl_add_u64 v[76:77], s[10:11], 0, v[76:77]
	v_lshl_add_u64 v[82:83], v[76:77], 0, v[164:165]
	global_store_dwordx2 v[82:83], v[80:81], off
	v_mul_f32_e32 v1, 0x41800000, v72
	v_mul_f32_e32 v80, 0x41800000, v73
	v_mov_b32_e32 v72, 0
	v_mov_b32_e32 v73, 0
	v_mul_f32_e32 v81, 0x41800000, v74
	v_mul_f32_e32 v84, 0x41800000, v75
	v_add_u32_e32 v74, 0x80, v166
	v_ashrrev_i32_e32 v75, 31, v74
	s_waitcnt vmcnt(15)
	v_lshlrev_b32_e32 v85, 16, v208
	v_and_b32_e32 v76, 0xffff0000, v208
	v_lshlrev_b32_e32 v87, 16, v210
	v_and_b32_e32 v78, 0xffff0000, v210
	v_mul_f32_e32 v1, v1, v85
	v_mul_f32_e32 v76, v80, v76
	v_mul_f32_e32 v68, v68, v87
	v_mul_f32_e32 v69, v69, v78
	v_cvt_pk_fp8_f32 v72, v1, v76
	v_cvt_pk_fp8_f32 v73, v68, v69
	v_lshlrev_b32_e32 v86, 16, v209
	v_and_b32_e32 v77, 0xffff0000, v209
	v_lshlrev_b32_e32 v88, 16, v211
	v_and_b32_e32 v79, 0xffff0000, v211
	v_mul_f32_e32 v80, v81, v86
	v_mul_f32_e32 v77, v84, v77
	v_mul_f32_e32 v1, v70, v88
	v_mul_f32_e32 v68, v71, v79
	v_cvt_pk_fp8_f32 v72, v80, v77 op_sel:[0,0,1]
	v_cvt_pk_fp8_f32 v73, v1, v68 op_sel:[0,0,1]
	v_lshlrev_b64 v[68:69], 12, v[74:75]
	v_lshl_add_u64 v[68:69], s[8:9], 0, v[68:69]
	v_lshl_add_u64 v[76:77], v[68:69], 0, v[2:3]
	global_store_dwordx2 v[82:83], v[72:73], off offset:128
	v_mul_f32_e32 v1, 0x41800000, v64
	v_mul_f32_e32 v72, 0x41800000, v65
	v_mov_b32_e32 v64, 0
	v_mov_b32_e32 v65, 0
	s_waitcnt vmcnt(15)
	v_lshlrev_b32_e32 v73, 16, v212
	v_and_b32_e32 v68, 0xffff0000, v212
	v_lshlrev_b32_e32 v79, 16, v214
	v_and_b32_e32 v70, 0xffff0000, v214
	v_mul_f32_e32 v1, v1, v73
	v_mul_f32_e32 v68, v72, v68
	v_mul_f32_e32 v60, v60, v79
	v_mul_f32_e32 v61, v61, v70
	v_cvt_pk_fp8_f32 v64, v1, v68
	v_cvt_pk_fp8_f32 v65, v60, v61
	v_lshlrev_b32_e32 v78, 16, v213
	v_and_b32_e32 v69, 0xffff0000, v213
	v_lshlrev_b32_e32 v80, 16, v215
	v_and_b32_e32 v71, 0xffff0000, v215
	v_mul_f32_e32 v66, v66, v78
	v_mul_f32_e32 v67, v67, v69
	v_mul_f32_e32 v1, v62, v80
	v_mul_f32_e32 v60, v63, v71
	v_cvt_pk_fp8_f32 v64, v66, v67 op_sel:[0,0,1]
	v_cvt_pk_fp8_f32 v65, v1, v60 op_sel:[0,0,1]
	v_lshlrev_b64 v[60:61], 11, v[74:75]
	v_lshl_add_u64 v[60:61], s[10:11], 0, v[60:61]
	v_lshl_add_u64 v[66:67], v[60:61], 0, v[164:165]
	global_store_dwordx2 v[66:67], v[64:65], off
	v_mul_f32_e32 v1, 0x41800000, v56
	v_mul_f32_e32 v64, 0x41800000, v57
	v_mov_b32_e32 v56, 0
	v_mov_b32_e32 v57, 0
	v_mul_f32_e32 v65, 0x41800000, v58
	v_mul_f32_e32 v68, 0x41800000, v59
	v_add_u32_e32 v58, 0x90, v166
	v_ashrrev_i32_e32 v59, 31, v58
	s_waitcnt vmcnt(15)
	v_lshlrev_b32_e32 v69, 16, v216
	v_and_b32_e32 v60, 0xffff0000, v216
	v_lshlrev_b32_e32 v71, 16, v218
	v_and_b32_e32 v62, 0xffff0000, v218
	v_mul_f32_e32 v1, v1, v69
	v_mul_f32_e32 v60, v64, v60
	v_mul_f32_e32 v52, v52, v71
	v_mul_f32_e32 v53, v53, v62
	v_cvt_pk_fp8_f32 v56, v1, v60
	v_cvt_pk_fp8_f32 v57, v52, v53
	v_lshlrev_b32_e32 v70, 16, v217
	v_and_b32_e32 v61, 0xffff0000, v217
	v_lshlrev_b32_e32 v72, 16, v219
	v_and_b32_e32 v63, 0xffff0000, v219
	v_mul_f32_e32 v64, v65, v70
	v_mul_f32_e32 v61, v68, v61
	v_mul_f32_e32 v1, v54, v72
	v_mul_f32_e32 v52, v55, v63
	v_cvt_pk_fp8_f32 v56, v64, v61 op_sel:[0,0,1]
	v_cvt_pk_fp8_f32 v57, v1, v52 op_sel:[0,0,1]
	v_lshlrev_b64 v[52:53], 12, v[58:59]
	v_lshl_add_u64 v[52:53], s[8:9], 0, v[52:53]
	v_lshl_add_u64 v[60:61], v[52:53], 0, v[2:3]
	global_store_dwordx2 v[66:67], v[56:57], off offset:128
	v_mul_f32_e32 v1, 0x41800000, v48
	v_mul_f32_e32 v56, 0x41800000, v49
	v_mov_b32_e32 v48, 0
	v_mov_b32_e32 v49, 0
	s_waitcnt vmcnt(15)
	v_lshlrev_b32_e32 v57, 16, v220
	v_and_b32_e32 v52, 0xffff0000, v220
	v_lshlrev_b32_e32 v63, 16, v222
	v_and_b32_e32 v54, 0xffff0000, v222
	v_mul_f32_e32 v1, v1, v57
	v_mul_f32_e32 v52, v56, v52
	v_mul_f32_e32 v44, v44, v63
	v_mul_f32_e32 v45, v45, v54
	v_cvt_pk_fp8_f32 v48, v1, v52
	v_cvt_pk_fp8_f32 v49, v44, v45
	v_lshlrev_b32_e32 v62, 16, v221
	v_and_b32_e32 v53, 0xffff0000, v221
	v_lshlrev_b32_e32 v64, 16, v223
	v_and_b32_e32 v55, 0xffff0000, v223
	v_mul_f32_e32 v50, v50, v62
	v_mul_f32_e32 v51, v51, v53
	v_mul_f32_e32 v1, v46, v64
	v_mul_f32_e32 v44, v47, v55
	v_cvt_pk_fp8_f32 v48, v50, v51 op_sel:[0,0,1]
	v_cvt_pk_fp8_f32 v49, v1, v44 op_sel:[0,0,1]
	v_lshlrev_b64 v[44:45], 11, v[58:59]
	v_lshl_add_u64 v[44:45], s[10:11], 0, v[44:45]
	v_lshl_add_u64 v[50:51], v[44:45], 0, v[164:165]
	global_store_dwordx2 v[50:51], v[48:49], off
	v_mul_f32_e32 v1, 0x41800000, v40
	v_mul_f32_e32 v48, 0x41800000, v41
	v_mov_b32_e32 v40, 0
	v_mov_b32_e32 v41, 0
	v_mul_f32_e32 v49, 0x41800000, v42
	v_mul_f32_e32 v52, 0x41800000, v43
	v_add_u32_e32 v42, 0xa0, v166
	v_ashrrev_i32_e32 v43, 31, v42
	s_waitcnt vmcnt(15)
	v_lshlrev_b32_e32 v53, 16, v224
	v_and_b32_e32 v44, 0xffff0000, v224
	v_lshlrev_b32_e32 v55, 16, v226
	v_and_b32_e32 v46, 0xffff0000, v226
	v_mul_f32_e32 v1, v1, v53
	v_mul_f32_e32 v44, v48, v44
	v_mul_f32_e32 v36, v36, v55
	v_mul_f32_e32 v37, v37, v46
	v_cvt_pk_fp8_f32 v40, v1, v44
	v_cvt_pk_fp8_f32 v41, v36, v37
	v_lshlrev_b32_e32 v54, 16, v225
	v_and_b32_e32 v45, 0xffff0000, v225
	v_lshlrev_b32_e32 v56, 16, v227
	v_and_b32_e32 v47, 0xffff0000, v227
	v_mul_f32_e32 v48, v49, v54
	v_mul_f32_e32 v45, v52, v45
	v_mul_f32_e32 v1, v38, v56
	v_mul_f32_e32 v36, v39, v47
	v_cvt_pk_fp8_f32 v40, v48, v45 op_sel:[0,0,1]
	v_cvt_pk_fp8_f32 v41, v1, v36 op_sel:[0,0,1]
	v_lshlrev_b64 v[36:37], 12, v[42:43]
	v_lshl_add_u64 v[36:37], s[8:9], 0, v[36:37]
	v_lshl_add_u64 v[44:45], v[36:37], 0, v[2:3]
	global_store_dwordx2 v[50:51], v[40:41], off offset:128
	v_mul_f32_e32 v1, 0x41800000, v32
	v_mul_f32_e32 v40, 0x41800000, v33
	v_mov_b32_e32 v32, 0
	v_mov_b32_e32 v33, 0
	s_waitcnt vmcnt(15)
	v_lshlrev_b32_e32 v41, 16, v234
	v_and_b32_e32 v36, 0xffff0000, v234
	v_lshlrev_b32_e32 v47, 16, v236
	v_and_b32_e32 v38, 0xffff0000, v236
	v_mul_f32_e32 v1, v1, v41
	v_mul_f32_e32 v36, v40, v36
	v_mul_f32_e32 v28, v28, v47
	v_mul_f32_e32 v29, v29, v38
	v_cvt_pk_fp8_f32 v32, v1, v36
	v_cvt_pk_fp8_f32 v33, v28, v29
	v_lshlrev_b32_e32 v46, 16, v235
	v_and_b32_e32 v37, 0xffff0000, v235
	v_lshlrev_b32_e32 v48, 16, v237
	v_and_b32_e32 v39, 0xffff0000, v237
	v_mul_f32_e32 v34, v34, v46
	v_mul_f32_e32 v35, v35, v37
	v_mul_f32_e32 v1, v30, v48
	v_mul_f32_e32 v28, v31, v39
	v_cvt_pk_fp8_f32 v32, v34, v35 op_sel:[0,0,1]
	v_cvt_pk_fp8_f32 v33, v1, v28 op_sel:[0,0,1]
	v_lshlrev_b64 v[28:29], 11, v[42:43]
	v_lshl_add_u64 v[28:29], s[10:11], 0, v[28:29]
	v_lshl_add_u64 v[34:35], v[28:29], 0, v[164:165]
	global_store_dwordx2 v[34:35], v[32:33], off
	v_mul_f32_e32 v1, 0x41800000, v24
	v_mul_f32_e32 v32, 0x41800000, v25
	v_mov_b32_e32 v24, 0
	v_mov_b32_e32 v25, 0
	v_mul_f32_e32 v33, 0x41800000, v26
	v_mul_f32_e32 v36, 0x41800000, v27
	v_add_u32_e32 v26, 0xb0, v166
	v_ashrrev_i32_e32 v27, 31, v26
	s_waitcnt vmcnt(15)
	v_lshlrev_b32_e32 v37, 16, v238
	v_and_b32_e32 v28, 0xffff0000, v238
	v_lshlrev_b32_e32 v39, 16, v240
	v_and_b32_e32 v30, 0xffff0000, v240
	v_mul_f32_e32 v1, v1, v37
	v_mul_f32_e32 v28, v32, v28
	v_mul_f32_e32 v20, v20, v39
	v_mul_f32_e32 v21, v21, v30
	v_cvt_pk_fp8_f32 v24, v1, v28
	v_cvt_pk_fp8_f32 v25, v20, v21
	v_lshlrev_b32_e32 v38, 16, v239
	v_and_b32_e32 v29, 0xffff0000, v239
	v_lshlrev_b32_e32 v40, 16, v241
	v_and_b32_e32 v31, 0xffff0000, v241
	v_mul_f32_e32 v32, v33, v38
	v_mul_f32_e32 v29, v36, v29
	v_mul_f32_e32 v1, v22, v40
	v_mul_f32_e32 v20, v23, v31
	v_cvt_pk_fp8_f32 v24, v32, v29 op_sel:[0,0,1]
	v_cvt_pk_fp8_f32 v25, v1, v20 op_sel:[0,0,1]
	v_lshlrev_b64 v[20:21], 12, v[26:27]
	v_lshl_add_u64 v[20:21], s[8:9], 0, v[20:21]
	v_lshl_add_u64 v[2:3], v[20:21], 0, v[2:3]
	global_store_dwordx2 v[34:35], v[24:25], off offset:128
	v_mul_f32_e32 v1, 0x41800000, v16
	v_mul_f32_e32 v24, 0x41800000, v17
	v_mov_b32_e32 v16, 0
	v_mov_b32_e32 v17, 0
	s_waitcnt vmcnt(15)
	v_lshlrev_b32_e32 v25, 16, v244
	v_and_b32_e32 v20, 0xffff0000, v244
	v_lshlrev_b32_e32 v29, 16, v246
	v_and_b32_e32 v22, 0xffff0000, v246
	v_mul_f32_e32 v1, v1, v25
	v_mul_f32_e32 v20, v24, v20
	v_mul_f32_e32 v12, v12, v29
	v_mul_f32_e32 v13, v13, v22
	v_cvt_pk_fp8_f32 v16, v1, v20
	v_cvt_pk_fp8_f32 v17, v12, v13
	v_lshlrev_b32_e32 v28, 16, v245
	v_and_b32_e32 v21, 0xffff0000, v245
	v_lshlrev_b32_e32 v30, 16, v247
	v_and_b32_e32 v23, 0xffff0000, v247
	v_mul_f32_e32 v18, v18, v28
	v_mul_f32_e32 v19, v19, v21
	v_mul_f32_e32 v1, v14, v30
	v_mul_f32_e32 v12, v15, v23
	v_cvt_pk_fp8_f32 v16, v18, v19 op_sel:[0,0,1]
	v_cvt_pk_fp8_f32 v17, v1, v12 op_sel:[0,0,1]
	v_lshlrev_b64 v[12:13], 11, v[26:27]
	v_lshl_add_u64 v[12:13], s[10:11], 0, v[12:13]
	v_lshl_add_u64 v[18:19], v[12:13], 0, v[164:165]
	global_store_dwordx2 v[18:19], v[16:17], off
	v_mul_f32_e32 v1, 0x41800000, v8
	v_mul_f32_e32 v8, 0x41800000, v9
	v_mul_f32_e32 v9, 0x41800000, v10
	v_mul_f32_e32 v10, 0x41800000, v11
	v_mov_b32_e32 v2, 0
	v_mov_b32_e32 v3, 0
	s_waitcnt vmcnt(15)
	v_lshlrev_b32_e32 v11, 16, v248
	v_and_b32_e32 v12, 0xffff0000, v248
	v_lshlrev_b32_e32 v17, 16, v250
	v_and_b32_e32 v14, 0xffff0000, v250
	v_mul_f32_e32 v1, v1, v11
	v_mul_f32_e32 v8, v8, v12
	v_mul_f32_e32 v4, v4, v17
	v_mul_f32_e32 v5, v5, v14
	v_cvt_pk_fp8_f32 v2, v1, v8
	v_cvt_pk_fp8_f32 v3, v4, v5
	v_lshlrev_b32_e32 v16, 16, v249
	v_and_b32_e32 v13, 0xffff0000, v249
	v_lshlrev_b32_e32 v20, 16, v251
	v_and_b32_e32 v15, 0xffff0000, v251
	v_mul_f32_e32 v9, v9, v16
	v_mul_f32_e32 v10, v10, v13
	v_mul_f32_e32 v1, v6, v20
	v_mul_f32_e32 v4, v7, v15
	v_cvt_pk_fp8_f32 v2, v9, v10 op_sel:[0,0,1]
	v_cvt_pk_fp8_f32 v3, v1, v4 op_sel:[0,0,1]
	global_store_dwordx2 v[18:19], v[2:3], off offset:128
	s_cbranch_vccnz .LBB0_648
	s_andn2_b64 vcc, exec, s[4:5]
	s_cbranch_vccnz .LBB0_647
	s_barrier
	s_branch .LBB0_647
